# diff final pass register-resident (one load round trip), odd-pass epilogue loads hoisted, on top of v72
# speedup vs baseline: 1.0170x; 1.0054x over previous
; #define SBAR() __builtin_amdgcn_sched_barrier(0)
; __device__ __forceinline__ int crow(int r, int hi) { return (r & 3) + 8 * (r >> 2) + 4 * hi; }
; template <int D0> __device__ __forceinline__ void pv_one(f32x16& od, int vb, bf16x8 pa0, bf16x8 pa1, bf16x8 pa2, bf16x8 pa3) {
;   const s16x4 l0 = tr_read<v_rd_off(D0, 0, 0)>(vb), h0 = tr_read<v_rd_off(D0, 0, 1)>(vb), l1 = tr_read<v_rd_off(D0, 1, 0)>(vb), h1 = tr_read<v_rd_off(D0, 1, 1)>(vb);
;   const s16x4 l2 = tr_read<v_rd_off(D0, 2, 0)>(vb), h2 = tr_read<v_rd_off(D0, 2, 1)>(vb), l3 = tr_read<v_rd_off(D0, 3, 0)>(vb), h3 = tr_read<v_rd_off(D0, 3, 1)>(vb);
;   asm volatile("s_waitcnt lgkmcnt(0)" ::: "memory"); SBAR();
;     ...
;   od = __builtin_amdgcn_mfma_f32_32x32x16_bf16(pa0, PK(l0, h0), od, 0, 0, 0);
;   od = __builtin_amdgcn_mfma_f32_32x32x16_bf16(pa1, PK(l1, h1), od, 0, 0, 0);
;   od = __builtin_amdgcn_mfma_f32_32x32x16_bf16(pa2, PK(l2, h2), od, 0, 0, 0);
;   od = __builtin_amdgcn_mfma_f32_32x32x16_bf16(pa3, PK(l3, h3), od, 0, 0, 0);
;     ...
; }
; __device__ __forceinline__ void pv_d0(f32x16* o, int vb, bf16x8 pa0, bf16x8 pa1, bf16x8 pa2, bf16x8 pa3) {
;   pv_one<0>(o[0], vb, pa0, pa1, pa2, pa3); pv_one<1>(o[1], vb, pa0, pa1, pa2, pa3); pv_one<2>(o[2], vb, pa0, pa1, pa2, pa3); pv_one<3>(o[3], vb, pa0, pa1, pa2, pa3);
; __device__ __forceinline__ void attn_core_pair(f32x16 (&o)[4], const bf16_t* __restrict__ Qb, const bf16_t* __restrict__ Kh, const bf16_t* __restrict__ Vh, const int seq, const float C, const float thr_raw, char* lds) {
;     ...
; #pragma unroll
;   for (int r = 0; r < 16; ++r) { const float rl = __builtin_amdgcn_rcpf(l_l[crow(r, hi)]);
; #pragma unroll
;     for (int d = 0; d < 4; ++d) o[d][r] *= rl; }
; __global__ void __launch_bounds__(512, 2) fwd_megakernel(const Params p) {
;     ...
;       f32x4* sl8 = sl + 8 * 64;
;       if ((pass & 1) == 0) {
.LBB0_407:
	s_or_b64 exec, exec, s[28:29]
	s_lshl_b32 s28, s55, 4
	s_and_b32 s28, s28, 0xff0
	s_lshl_b32 s29, s56, 3
	s_or_b32 s28, s28, s29
	s_add_i32 s38, s38, 0x8000
	s_cmp_lg_u32 s16, 2
	s_cselect_b32 s16, s38, 0
	v_add_u32_e32 v102, s16, v204
	ds_read_b64_tr_b16 v[82:83], v102 offset:0
	ds_read_b64_tr_b16 v[84:85], v102 offset:0x800
	ds_read_b64_tr_b16 v[86:87], v102 offset:0x1000
	ds_read_b64_tr_b16 v[88:89], v102 offset:0x1800
	ds_read_b64_tr_b16 v[90:91], v102 offset:0x2000
	ds_read_b64_tr_b16 v[92:93], v102 offset:0x2800
	ds_read_b64_tr_b16 v[94:95], v102 offset:0x3000
	ds_read_b64_tr_b16 v[96:97], v102 offset:0x3800
	v_add_u32_e32 v80, s28, v193
	s_waitcnt lgkmcnt(0)
	v_lshl_or_b32 v80, v80, 14, v156
	v_mov_b32_e32 v81, v159
	v_lshl_add_u64 v[80:81], s[18:19], 0, v[80:81]
	s_waitcnt lgkmcnt(3)
	v_mfma_f32_32x32x16_bf16 v[48:63], v[64:67], v[82:85], v[48:63]
	ds_read_b64_tr_b16 v[82:83], v102 offset:0x200
	ds_read_b64_tr_b16 v[84:85], v102 offset:0xa00
	s_waitcnt lgkmcnt(2)
	v_mfma_f32_32x32x16_bf16 v[48:63], v[68:71], v[86:89], v[48:63]
	ds_read_b64_tr_b16 v[86:87], v102 offset:0x1200
	ds_read_b64_tr_b16 v[88:89], v102 offset:0x1a00
	s_waitcnt lgkmcnt(1)
	v_mfma_f32_32x32x16_bf16 v[48:63], v[76:79], v[90:93], v[48:63]
	ds_read_b64_tr_b16 v[90:91], v102 offset:0x2200
	ds_read_b64_tr_b16 v[92:93], v102 offset:0x2a00
	ds_read_b64_tr_b16 v[98:99], v102 offset:0x3200
	ds_read_b64_tr_b16 v[100:101], v102 offset:0x3a00
	s_waitcnt lgkmcnt(0)
	s_waitcnt lgkmcnt(0)
	v_mfma_f32_32x32x16_bf16 v[48:63], v[72:75], v[94:97], v[48:63]
	v_mfma_f32_32x32x16_bf16 v[32:47], v[64:67], v[82:85], v[32:47]
	ds_read_b64_tr_b16 v[82:83], v102 offset:0x400
	ds_read_b64_tr_b16 v[84:85], v102 offset:0xc00
	v_mfma_f32_32x32x16_bf16 v[32:47], v[68:71], v[86:89], v[32:47]
	ds_read_b64_tr_b16 v[86:87], v102 offset:0x1400
	ds_read_b64_tr_b16 v[88:89], v102 offset:0x1c00
	v_mfma_f32_32x32x16_bf16 v[32:47], v[76:79], v[90:93], v[32:47]
	ds_read_b64_tr_b16 v[90:91], v102 offset:0x2400
	ds_read_b64_tr_b16 v[92:93], v102 offset:0x2c00
	ds_read_b64_tr_b16 v[94:95], v102 offset:0x3400
	ds_read_b64_tr_b16 v[96:97], v102 offset:0x3c00
	s_waitcnt lgkmcnt(0)
	v_mfma_f32_32x32x16_bf16 v[32:47], v[72:75], v[98:101], v[32:47]
	v_mfma_f32_32x32x16_bf16 v[16:31], v[64:67], v[82:85], v[16:31]
	ds_read_b64_tr_b16 v[82:83], v102 offset:0x600
	ds_read_b64_tr_b16 v[84:85], v102 offset:0xe00
	v_mfma_f32_32x32x16_bf16 v[16:31], v[68:71], v[86:89], v[16:31]
	ds_read_b64_tr_b16 v[86:87], v102 offset:0x1600
	ds_read_b64_tr_b16 v[88:89], v102 offset:0x1e00
	v_mfma_f32_32x32x16_bf16 v[16:31], v[76:79], v[90:93], v[16:31]
	ds_read_b64_tr_b16 v[90:91], v102 offset:0x2600
	ds_read_b64_tr_b16 v[92:93], v102 offset:0x2e00
	ds_read_b64_tr_b16 v[98:99], v102 offset:0x3600
	ds_read_b64_tr_b16 v[100:101], v102 offset:0x3e00
	s_waitcnt lgkmcnt(0)
	v_mfma_f32_32x32x16_bf16 v[16:31], v[72:75], v[94:97], v[16:31]
	v_mfma_f32_32x32x16_bf16 v[0:15], v[64:67], v[82:85], v[0:15]
	v_add_u32_e32 v106, v195, v202
	s_barrier
	ds_read_b128 v[94:97], v106
	ds_read_b128 v[102:105], v106 offset:32
	s_cmp_lg_u32 s54, 0
	s_mov_b64 s[28:29], -1
	v_mfma_f32_32x32x16_bf16 v[0:15], v[68:71], v[86:89], v[0:15]
	s_waitcnt lgkmcnt(1)
	v_rcp_f32_e32 v82, v94
	v_rcp_f32_e32 v83, v95
	v_rcp_f32_e32 v84, v96
	v_rcp_f32_e32 v85, v97
	s_waitcnt lgkmcnt(0)
	v_rcp_f32_e32 v86, v102
	v_rcp_f32_e32 v87, v103
	v_rcp_f32_e32 v88, v104
	v_mfma_f32_32x32x16_bf16 v[0:15], v[76:79], v[90:93], v[0:15]
	v_rcp_f32_e32 v89, v105
	ds_read_b128 v[68:71], v106 offset:64
	ds_read_b128 v[76:79], v106 offset:96
	v_pk_mul_f32 v[64:65], v[82:83], v[48:49]
	v_pk_mul_f32 v[66:67], v[84:85], v[50:51]
	v_pk_mul_f32 v[50:51], v[86:87], v[36:37]
	v_pk_mul_f32 v[32:33], v[82:83], v[32:33]
	v_pk_mul_f32 v[16:17], v[82:83], v[16:17]
	v_mfma_f32_32x32x16_bf16 v[0:15], v[72:75], v[98:101], v[0:15]
	v_mul_f32_e64 v34, v84, v34
	v_mul_f32_e64 v35, v85, v35
	v_mul_f32_e64 v18, v84, v18
	v_mul_f32_e64 v19, v85, v19
	v_mul_f32_e64 v52, v86, v52
	v_mul_f32_e64 v53, v87, v53
	v_pk_mul_f32 v[20:21], v[86:87], v[20:21]
	v_pk_mul_f32 v[54:55], v[88:89], v[54:55]
	s_waitcnt lgkmcnt(0)
	s_barrier
	s_nop 1
	v_pk_mul_f32 v[48:49], v[82:83], v[0:1]
	v_pk_mul_f32 v[36:37], v[84:85], v[2:3]
	v_pk_mul_f32 v[0:1], v[86:87], v[4:5]
	v_rcp_f32_e32 v2, v68
	v_rcp_f32_e32 v3, v69
	v_pk_mul_f32 v[4:5], v[88:89], v[6:7]
	v_rcp_f32_e32 v6, v70
	v_rcp_f32_e32 v7, v71
	v_pk_mul_f32 v[68:69], v[88:89], v[38:39]
	v_pk_mul_f32 v[38:39], v[88:89], v[22:23]
	v_pk_mul_f32 v[56:57], v[2:3], v[56:57]
	v_pk_mul_f32 v[40:41], v[2:3], v[40:41]
	v_pk_mul_f32 v[22:23], v[2:3], v[24:25]
	v_pk_mul_f32 v[2:3], v[2:3], v[8:9]
	v_pk_mul_f32 v[58:59], v[6:7], v[58:59]
	v_rcp_f32_e32 v8, v76
	v_rcp_f32_e32 v9, v77
	v_pk_mul_f32 v[42:43], v[6:7], v[42:43]
	v_pk_mul_f32 v[24:25], v[6:7], v[26:27]
	v_pk_mul_f32 v[6:7], v[6:7], v[10:11]
	v_rcp_f32_e32 v10, v78
	v_rcp_f32_e32 v11, v79
	v_pk_mul_f32 v[60:61], v[8:9], v[60:61]
	v_pk_mul_f32 v[44:45], v[8:9], v[44:45]
	v_pk_mul_f32 v[26:27], v[8:9], v[28:29]
	v_pk_mul_f32 v[8:9], v[8:9], v[12:13]
	v_pk_mul_f32 v[62:63], v[10:11], v[62:63]
	v_pk_mul_f32 v[28:29], v[10:11], v[46:47]
	v_pk_mul_f32 v[12:13], v[10:11], v[30:31]
	v_pk_mul_f32 v[10:11], v[10:11], v[14:15]
	v_lshl_add_u64 v[14:15], v[80:81], 0, s[22:23]
	s_cbranch_scc0 .LBB0_409
; #define EPI_FENCE() asm volatile("" ::: "memory")
; __global__ void __launch_bounds__(512, 2) fwd_megakernel(const Params p) {
;     ...
;           for (int q = 0; q < 4; q += 2) { const u32x4 w = __builtin_bit_cast(u32x4, sl8[(d * 2 + (q >> 1)) * 64]);
;             const f32x4 a = {__uint_as_float(w.x << 16), __uint_as_float(w.x & 0xffff0000u), __uint_as_float(w.y << 16), __uint_as_float(w.y & 0xffff0000u)};
;             const f32x4 b = {__uint_as_float(w.z << 16), __uint_as_float(w.z & 0xffff0000u), __uint_as_float(w.w << 16), __uint_as_float(w.w & 0xffff0000u)};
;             sl[(d * 4 + q) * 64] = O4(d, q) - lam * a; sl[(d * 4 + q + 1) * 64] = O4(d, q + 1) - lam * b; }
;           EPI_FENCE(); }
	v_add_co_u32_e32 v30, vcc, s49, v80
	s_nop 1
	v_addc_co_u32_e32 v31, vcc, 0, v81, vcc
	v_add_co_u32_e32 v150, vcc, s51, v80
	s_nop 1
	v_addc_co_u32_e32 v151, vcc, 0, v81, vcc
	global_load_dwordx4 v[96:99], v[14:15], off
	global_load_dwordx4 v[100:103], v[30:31], off offset:1024
	global_load_dwordx4 v[104:107], v[30:31], off offset:2048
	global_load_dwordx4 v[108:111], v[30:31], off offset:3072
	global_load_dwordx4 v[112:115], v[150:151], off
	global_load_dwordx4 v[116:119], v[150:151], off offset:1024
	global_load_dwordx4 v[120:123], v[150:151], off offset:2048
	global_load_dwordx4 v[124:127], v[150:151], off offset:3072
	s_nop 0
	s_mov_b64 s[28:29], 0
	s_waitcnt vmcnt(7)
	v_lshlrev_b32_e32 v46, 16, v96
	v_and_b32_e32 v47, 0xffff0000, v96
	v_lshlrev_b32_e32 v70, 16, v97
	v_and_b32_e32 v71, 0xffff0000, v97
	v_lshlrev_b32_e32 v78, 16, v98
	v_and_b32_e32 v79, 0xffff0000, v98
	v_lshlrev_b32_e32 v82, 16, v99
	v_and_b32_e32 v83, 0xffff0000, v99
	v_pk_fma_f32 v[72:73], v[186:187], v[70:71], v[66:67] op_sel_hi:[0,1,1] neg_lo:[1,0,0] neg_hi:[1,0,0]
	v_pk_fma_f32 v[70:71], v[186:187], v[46:47], v[64:65] op_sel_hi:[0,1,1] neg_lo:[1,0,0] neg_hi:[1,0,0]
	s_waitcnt vmcnt(6)
	v_lshlrev_b32_e32 v46, 16, v100
	v_and_b32_e32 v47, 0xffff0000, v100
	v_lshlrev_b32_e32 v74, 16, v101
	v_and_b32_e32 v75, 0xffff0000, v101
	v_pk_fma_f32 v[84:85], v[186:187], v[82:83], v[54:55] op_sel_hi:[0,1,1] neg_lo:[1,0,0] neg_hi:[1,0,0]
	v_pk_fma_f32 v[82:83], v[186:187], v[78:79], v[52:53] op_sel_hi:[0,1,1] neg_lo:[1,0,0] neg_hi:[1,0,0]
	v_lshlrev_b32_e32 v78, 16, v102
	v_and_b32_e32 v79, 0xffff0000, v102
	v_lshlrev_b32_e32 v76, 16, v103
	v_and_b32_e32 v77, 0xffff0000, v103
	global_store_dwordx4 v[80:81], v[70:73], off
	global_store_dwordx4 v[80:81], v[82:85], off offset:1024
	v_pk_fma_f32 v[76:77], v[186:187], v[76:77], v[62:63] op_sel_hi:[0,1,1] neg_lo:[1,0,0] neg_hi:[1,0,0]
	v_pk_fma_f32 v[72:73], v[186:187], v[74:75], v[58:59] op_sel_hi:[0,1,1] neg_lo:[1,0,0] neg_hi:[1,0,0]
	v_pk_fma_f32 v[70:71], v[186:187], v[46:47], v[56:57] op_sel_hi:[0,1,1] neg_lo:[1,0,0] neg_hi:[1,0,0]
	v_pk_fma_f32 v[74:75], v[186:187], v[78:79], v[60:61] op_sel_hi:[0,1,1] neg_lo:[1,0,0] neg_hi:[1,0,0]
	global_store_dwordx4 v[80:81], v[70:73], off offset:2048
	global_store_dwordx4 v[80:81], v[74:77], off offset:3072
	v_add_co_u32_e32 v46, vcc, s50, v80
	s_waitcnt vmcnt(9)
	v_lshlrev_b32_e32 v82, 16, v104
	v_and_b32_e32 v83, 0xffff0000, v104
	v_lshlrev_b32_e32 v70, 16, v105
	v_and_b32_e32 v71, 0xffff0000, v105
	v_addc_co_u32_e32 v47, vcc, 0, v81, vcc
	v_lshlrev_b32_e32 v84, 16, v106
	v_and_b32_e32 v85, 0xffff0000, v106
	v_lshlrev_b32_e32 v86, 16, v107
	v_and_b32_e32 v87, 0xffff0000, v107
	s_waitcnt vmcnt(8)
	v_lshlrev_b32_e32 v88, 16, v108
	v_and_b32_e32 v89, 0xffff0000, v108
	v_lshlrev_b32_e32 v90, 16, v109
	v_and_b32_e32 v91, 0xffff0000, v109
	v_lshlrev_b32_e32 v92, 16, v110
	v_and_b32_e32 v93, 0xffff0000, v110
	v_lshlrev_b32_e32 v94, 16, v111
	v_and_b32_e32 v95, 0xffff0000, v111
	v_pk_fma_f32 v[72:73], v[186:187], v[70:71], v[34:35] op_sel_hi:[0,1,1] neg_lo:[1,0,0] neg_hi:[1,0,0]
	v_pk_fma_f32 v[70:71], v[186:187], v[82:83], v[32:33] op_sel_hi:[0,1,1] neg_lo:[1,0,0] neg_hi:[1,0,0]
	v_add_co_u32_e32 v78, vcc, s51, v80
	v_pk_fma_f32 v[76:77], v[186:187], v[86:87], v[68:69] op_sel_hi:[0,1,1] neg_lo:[1,0,0] neg_hi:[1,0,0]
	v_pk_fma_f32 v[74:75], v[186:187], v[84:85], v[50:51] op_sel_hi:[0,1,1] neg_lo:[1,0,0] neg_hi:[1,0,0]
	v_pk_fma_f32 v[84:85], v[186:187], v[90:91], v[42:43] op_sel_hi:[0,1,1] neg_lo:[1,0,0] neg_hi:[1,0,0]
	v_pk_fma_f32 v[82:83], v[186:187], v[88:89], v[40:41] op_sel_hi:[0,1,1] neg_lo:[1,0,0] neg_hi:[1,0,0]
	v_pk_fma_f32 v[88:89], v[186:187], v[94:95], v[28:29] op_sel_hi:[0,1,1] neg_lo:[1,0,0] neg_hi:[1,0,0]
	v_pk_fma_f32 v[86:87], v[186:187], v[92:93], v[44:45] op_sel_hi:[0,1,1] neg_lo:[1,0,0] neg_hi:[1,0,0]
	global_store_dwordx4 v[46:47], v[70:73], off
	global_store_dwordx4 v[46:47], v[74:77], off offset:1024
	global_store_dwordx4 v[46:47], v[82:85], off offset:2048
	global_store_dwordx4 v[46:47], v[86:89], off offset:3072
	v_addc_co_u32_e32 v79, vcc, 0, v81, vcc
	s_waitcnt vmcnt(11)
; #define EPI_FENCE() asm volatile("" ::: "memory")
; __global__ void __launch_bounds__(512, 2) fwd_megakernel(const Params p) {
;     ...
;           for (int q = 0; q < 4; q += 2) { const u32x4 w = __builtin_bit_cast(u32x4, sl8[(d * 2 + (q >> 1)) * 64]);
;             const f32x4 a = {__uint_as_float(w.x << 16), __uint_as_float(w.x & 0xffff0000u), __uint_as_float(w.y << 16), __uint_as_float(w.y & 0xffff0000u)};
;             const f32x4 b = {__uint_as_float(w.z << 16), __uint_as_float(w.z & 0xffff0000u), __uint_as_float(w.w << 16), __uint_as_float(w.w & 0xffff0000u)};
;             sl[(d * 4 + q) * 64] = O4(d, q) - lam * a; sl[(d * 4 + q + 1) * 64] = O4(d, q + 1) - lam * b; }
;           EPI_FENCE(); }
	v_lshlrev_b32_e32 v46, 16, v112
	v_and_b32_e32 v47, 0xffff0000, v112
	v_lshlrev_b32_e32 v70, 16, v113
	v_and_b32_e32 v71, 0xffff0000, v113
	v_lshlrev_b32_e32 v82, 16, v114
	v_and_b32_e32 v83, 0xffff0000, v114
	v_lshlrev_b32_e32 v84, 16, v115
	v_and_b32_e32 v85, 0xffff0000, v115
	s_waitcnt vmcnt(10)
	v_lshlrev_b32_e32 v86, 16, v116
	v_and_b32_e32 v87, 0xffff0000, v116
	v_lshlrev_b32_e32 v88, 16, v117
	v_and_b32_e32 v89, 0xffff0000, v117
	v_lshlrev_b32_e32 v90, 16, v118
	v_and_b32_e32 v91, 0xffff0000, v118
	v_lshlrev_b32_e32 v92, 16, v119
	v_and_b32_e32 v93, 0xffff0000, v119
	v_pk_fma_f32 v[72:73], v[186:187], v[70:71], v[18:19] op_sel_hi:[0,1,1] neg_lo:[1,0,0] neg_hi:[1,0,0]
	v_pk_fma_f32 v[70:71], v[186:187], v[46:47], v[16:17] op_sel_hi:[0,1,1] neg_lo:[1,0,0] neg_hi:[1,0,0]
	v_pk_fma_f32 v[76:77], v[186:187], v[84:85], v[38:39] op_sel_hi:[0,1,1] neg_lo:[1,0,0] neg_hi:[1,0,0]
	v_pk_fma_f32 v[74:75], v[186:187], v[82:83], v[20:21] op_sel_hi:[0,1,1] neg_lo:[1,0,0] neg_hi:[1,0,0]
	v_pk_fma_f32 v[84:85], v[186:187], v[88:89], v[24:25] op_sel_hi:[0,1,1] neg_lo:[1,0,0] neg_hi:[1,0,0]
	v_pk_fma_f32 v[82:83], v[186:187], v[86:87], v[22:23] op_sel_hi:[0,1,1] neg_lo:[1,0,0] neg_hi:[1,0,0]
	v_pk_fma_f32 v[88:89], v[186:187], v[92:93], v[12:13] op_sel_hi:[0,1,1] neg_lo:[1,0,0] neg_hi:[1,0,0]
	v_pk_fma_f32 v[86:87], v[186:187], v[90:91], v[26:27] op_sel_hi:[0,1,1] neg_lo:[1,0,0] neg_hi:[1,0,0]
	global_store_dwordx4 v[14:15], v[70:73], off
	global_store_dwordx4 v[30:31], v[74:77], off offset:1024
	global_store_dwordx4 v[30:31], v[82:85], off offset:2048
	global_store_dwordx4 v[30:31], v[86:89], off offset:3072
	s_waitcnt vmcnt(13)
	v_lshlrev_b32_e32 v30, 16, v120
	v_and_b32_e32 v31, 0xffff0000, v120
	v_lshlrev_b32_e32 v46, 16, v121
	v_and_b32_e32 v47, 0xffff0000, v121
	v_lshlrev_b32_e32 v82, 16, v122
	v_and_b32_e32 v83, 0xffff0000, v122
	v_lshlrev_b32_e32 v84, 16, v123
	v_and_b32_e32 v85, 0xffff0000, v123
	s_waitcnt vmcnt(12)
	v_lshlrev_b32_e32 v86, 16, v124
	v_and_b32_e32 v87, 0xffff0000, v124
	v_lshlrev_b32_e32 v88, 16, v125
	v_and_b32_e32 v89, 0xffff0000, v125
	v_lshlrev_b32_e32 v90, 16, v126
	v_and_b32_e32 v91, 0xffff0000, v126
	v_lshlrev_b32_e32 v92, 16, v127
	v_and_b32_e32 v93, 0xffff0000, v127
	v_pk_fma_f32 v[72:73], v[186:187], v[46:47], v[36:37] op_sel_hi:[0,1,1] neg_lo:[1,0,0] neg_hi:[1,0,0]
	v_pk_fma_f32 v[70:71], v[186:187], v[30:31], v[48:49] op_sel_hi:[0,1,1] neg_lo:[1,0,0] neg_hi:[1,0,0]
	v_pk_fma_f32 v[76:77], v[186:187], v[84:85], v[4:5] op_sel_hi:[0,1,1] neg_lo:[1,0,0] neg_hi:[1,0,0]
	v_pk_fma_f32 v[74:75], v[186:187], v[82:83], v[0:1] op_sel_hi:[0,1,1] neg_lo:[1,0,0] neg_hi:[1,0,0]
	v_pk_fma_f32 v[84:85], v[186:187], v[88:89], v[6:7] op_sel_hi:[0,1,1] neg_lo:[1,0,0] neg_hi:[1,0,0]
	v_pk_fma_f32 v[82:83], v[186:187], v[86:87], v[2:3] op_sel_hi:[0,1,1] neg_lo:[1,0,0] neg_hi:[1,0,0]
	v_pk_fma_f32 v[88:89], v[186:187], v[92:93], v[10:11] op_sel_hi:[0,1,1] neg_lo:[1,0,0] neg_hi:[1,0,0]
	v_pk_fma_f32 v[86:87], v[186:187], v[90:91], v[8:9] op_sel_hi:[0,1,1] neg_lo:[1,0,0] neg_hi:[1,0,0]
	global_store_dwordx4 v[78:79], v[70:73], off
	global_store_dwordx4 v[78:79], v[74:77], off offset:1024
	global_store_dwordx4 v[78:79], v[82:85], off offset:2048
	global_store_dwordx4 v[78:79], v[86:89], off offset:3072

; #define EPI_FENCE() asm volatile("" ::: "memory")
; __global__ void __launch_bounds__(512, 2) fwd_megakernel(const Params p) {
;     ...
;       { float ssq[16];
; #pragma unroll
;         for (int r = 0; r < 16; ++r) ssq[r] = 0.f;
; #pragma unroll 1
;         for (int d = 0; d < 4; ++d) {
; #pragma unroll
;           for (int q = 0; q < 4; ++q) { const f32x4 lo = scr[(d * 4 + q) * 64], hv = scr[4 * 1024 + (d * 4 + q) * 64];
; #pragma unroll
;             for (int j = 0; j < 4; ++j) ssq[4 * q + j] += lo[j] * lo[j] + hv[j] * hv[j]; }
;           EPI_FENCE(); }
.LBB0_413:
	v_ashrrev_i32_e32 v3, 31, v2
	v_lshlrev_b64 v[8:9], 14, v[2:3]
	v_lshl_add_u64 v[8:9], v[0:1], 0, v[8:9]
	s_mov_b64 s[0:1], 0
	v_mov_b32_e32 v18, 0
	v_mov_b32_e32 v19, v157
	v_mov_b32_e32 v24, 0
	v_mov_b32_e32 v25, v157
	v_mov_b32_e32 v22, 0
	v_mov_b32_e32 v23, v157
	v_mov_b32_e32 v20, 0
	v_mov_b32_e32 v21, v157
	v_mov_b32_e32 v16, 0
	v_mov_b32_e32 v17, v157
	v_mov_b32_e32 v14, 0
	v_mov_b32_e32 v15, v157
	v_mov_b32_e32 v12, 0
	v_mov_b32_e32 v13, v157
	v_mov_b32_e32 v10, 0
	v_mov_b32_e32 v11, v157
	s_mov_b64 s[0:1], 0x0
	v_lshl_add_u64 v[30:31], v[8:9], 0, s[0:1]
	v_add_co_u32_e32 v58, vcc, s7, v30
	s_nop 1
	v_addc_co_u32_e32 v59, vcc, 0, v31, vcc
	v_add_co_u32_e32 v42, vcc, s10, v30
	s_nop 1
	v_addc_co_u32_e32 v43, vcc, 0, v31, vcc
	global_load_dwordx4 v[66:69], v[42:43], off
	global_load_dwordx4 v[74:77], v[42:43], off offset:1024
	global_load_dwordx4 v[82:85], v[42:43], off offset:2048
	global_load_dwordx4 v[90:93], v[42:43], off offset:3072
	global_load_dwordx4 v[62:65], v[58:59], off
	global_load_dwordx4 v[70:73], v[58:59], off offset:1024
	global_load_dwordx4 v[78:81], v[58:59], off offset:2048
	global_load_dwordx4 v[86:89], v[58:59], off offset:3072
	s_mov_b64 s[0:1], 0x1000
	v_lshl_add_u64 v[30:31], v[8:9], 0, s[0:1]
	v_add_co_u32_e32 v58, vcc, s7, v30
	s_nop 1
	v_addc_co_u32_e32 v59, vcc, 0, v31, vcc
	v_add_co_u32_e32 v42, vcc, s10, v30
	s_nop 1
	v_addc_co_u32_e32 v43, vcc, 0, v31, vcc
	global_load_dwordx4 v[98:101], v[42:43], off
	global_load_dwordx4 v[106:109], v[42:43], off offset:1024
	global_load_dwordx4 v[114:117], v[42:43], off offset:2048
	global_load_dwordx4 v[122:125], v[42:43], off offset:3072
	global_load_dwordx4 v[94:97], v[58:59], off
	global_load_dwordx4 v[102:105], v[58:59], off offset:1024
	global_load_dwordx4 v[110:113], v[58:59], off offset:2048
	global_load_dwordx4 v[118:121], v[58:59], off offset:3072
	s_mov_b64 s[0:1], 0x2000
	v_lshl_add_u64 v[30:31], v[8:9], 0, s[0:1]
	v_add_co_u32_e32 v58, vcc, s7, v30
	s_nop 1
	v_addc_co_u32_e32 v59, vcc, 0, v31, vcc
	v_add_co_u32_e32 v42, vcc, s10, v30
	s_nop 1
	v_addc_co_u32_e32 v43, vcc, 0, v31, vcc
	global_load_dwordx4 v[130:133], v[42:43], off
	global_load_dwordx4 v[138:141], v[42:43], off offset:1024
	global_load_dwordx4 v[146:149], v[42:43], off offset:2048
	global_load_dwordx4 v[162:165], v[42:43], off offset:3072
	global_load_dwordx4 v[126:129], v[58:59], off
	global_load_dwordx4 v[134:137], v[58:59], off offset:1024
	global_load_dwordx4 v[142:145], v[58:59], off offset:2048
	global_load_dwordx4 v[158:161], v[58:59], off offset:3072
	s_mov_b64 s[0:1], 0x3000
	v_lshl_add_u64 v[30:31], v[8:9], 0, s[0:1]
	v_add_co_u32_e32 v58, vcc, s7, v30
	s_nop 1
	v_addc_co_u32_e32 v59, vcc, 0, v31, vcc
	v_add_co_u32_e32 v42, vcc, s10, v30
	s_nop 1
	v_addc_co_u32_e32 v43, vcc, 0, v31, vcc
	global_load_dwordx4 v[170:173], v[42:43], off
	global_load_dwordx4 v[178:181], v[42:43], off offset:1024
	global_load_dwordx4 v[198:201], v[42:43], off offset:2048
	global_load_dwordx4 v[206:209], v[42:43], off offset:3072
	global_load_dwordx4 v[166:169], v[58:59], off
	global_load_dwordx4 v[174:177], v[58:59], off offset:1024
	global_load_dwordx4 v[182:185], v[58:59], off offset:2048
	global_load_dwordx4 v[202:205], v[58:59], off offset:3072
	s_waitcnt vmcnt(24)
	v_pk_mul_f32 v[220:221], v[66:67], v[66:67]
	v_pk_fma_f32 v[220:221], v[62:63], v[62:63], v[220:221]
	v_pk_add_f32 v[18:19], v[18:19], v[220:221]
	v_pk_mul_f32 v[220:221], v[68:69], v[68:69]
	v_pk_fma_f32 v[220:221], v[64:65], v[64:65], v[220:221]
	v_pk_add_f32 v[24:25], v[24:25], v[220:221]
	v_pk_mul_f32 v[220:221], v[74:75], v[74:75]
	v_pk_fma_f32 v[220:221], v[70:71], v[70:71], v[220:221]
	v_pk_add_f32 v[22:23], v[22:23], v[220:221]
	v_pk_mul_f32 v[220:221], v[76:77], v[76:77]
	v_pk_fma_f32 v[220:221], v[72:73], v[72:73], v[220:221]
	v_pk_add_f32 v[20:21], v[20:21], v[220:221]
	v_pk_mul_f32 v[220:221], v[82:83], v[82:83]
	v_pk_fma_f32 v[220:221], v[78:79], v[78:79], v[220:221]
	v_pk_add_f32 v[16:17], v[16:17], v[220:221]
	v_pk_mul_f32 v[220:221], v[84:85], v[84:85]
	v_pk_fma_f32 v[220:221], v[80:81], v[80:81], v[220:221]
	v_pk_add_f32 v[14:15], v[14:15], v[220:221]
	v_pk_mul_f32 v[220:221], v[90:91], v[90:91]
	v_pk_fma_f32 v[220:221], v[86:87], v[86:87], v[220:221]
	v_pk_add_f32 v[12:13], v[12:13], v[220:221]
	v_pk_mul_f32 v[220:221], v[92:93], v[92:93]
	v_pk_fma_f32 v[220:221], v[88:89], v[88:89], v[220:221]
	v_pk_add_f32 v[10:11], v[10:11], v[220:221]
	s_waitcnt vmcnt(16)
	v_pk_mul_f32 v[220:221], v[98:99], v[98:99]
	v_pk_fma_f32 v[220:221], v[94:95], v[94:95], v[220:221]
	v_pk_add_f32 v[18:19], v[18:19], v[220:221]
	v_pk_mul_f32 v[220:221], v[100:101], v[100:101]
	v_pk_fma_f32 v[220:221], v[96:97], v[96:97], v[220:221]
	v_pk_add_f32 v[24:25], v[24:25], v[220:221]
	v_pk_mul_f32 v[220:221], v[106:107], v[106:107]
	v_pk_fma_f32 v[220:221], v[102:103], v[102:103], v[220:221]
	v_pk_add_f32 v[22:23], v[22:23], v[220:221]
	v_pk_mul_f32 v[220:221], v[108:109], v[108:109]
	v_pk_fma_f32 v[220:221], v[104:105], v[104:105], v[220:221]
	v_pk_add_f32 v[20:21], v[20:21], v[220:221]
	v_pk_mul_f32 v[220:221], v[114:115], v[114:115]
	v_pk_fma_f32 v[220:221], v[110:111], v[110:111], v[220:221]
	v_pk_add_f32 v[16:17], v[16:17], v[220:221]
	v_pk_mul_f32 v[220:221], v[116:117], v[116:117]
	v_pk_fma_f32 v[220:221], v[112:113], v[112:113], v[220:221]
	v_pk_add_f32 v[14:15], v[14:15], v[220:221]
	v_pk_mul_f32 v[220:221], v[122:123], v[122:123]
	v_pk_fma_f32 v[220:221], v[118:119], v[118:119], v[220:221]
	v_pk_add_f32 v[12:13], v[12:13], v[220:221]
	v_pk_mul_f32 v[220:221], v[124:125], v[124:125]
	v_pk_fma_f32 v[220:221], v[120:121], v[120:121], v[220:221]
	v_pk_add_f32 v[10:11], v[10:11], v[220:221]
	s_waitcnt vmcnt(8)
; #define EPI_FENCE() asm volatile("" ::: "memory")
; __global__ void __launch_bounds__(512, 2) fwd_megakernel(const Params p) {
;     ...
;           for (int q = 0; q < 4; ++q) { const f32x4 lo = scr[(d * 4 + q) * 64], hv = scr[4 * 1024 + (d * 4 + q) * 64];
; #pragma unroll
;             for (int j = 0; j < 4; ++j) ssq[4 * q + j] += lo[j] * lo[j] + hv[j] * hv[j]; }
;           EPI_FENCE(); }
; #pragma unroll
;         for (int r = 0; r < 16; ++r) {
; #pragma unroll
;           for (int s = 16; s >= 1; s >>= 1) ssq[r] += __shfl_xor(ssq[r], s);
;           ssq[r] = rsqrtf(ssq[r] * (1.f / 256.f) + 1e-5f) * 0.8f; }
	v_pk_mul_f32 v[220:221], v[130:131], v[130:131]
	v_pk_fma_f32 v[220:221], v[126:127], v[126:127], v[220:221]
	v_pk_add_f32 v[18:19], v[18:19], v[220:221]
	v_pk_mul_f32 v[220:221], v[132:133], v[132:133]
	v_pk_fma_f32 v[220:221], v[128:129], v[128:129], v[220:221]
	v_pk_add_f32 v[24:25], v[24:25], v[220:221]
	v_pk_mul_f32 v[220:221], v[138:139], v[138:139]
	v_pk_fma_f32 v[220:221], v[134:135], v[134:135], v[220:221]
	v_pk_add_f32 v[22:23], v[22:23], v[220:221]
	v_pk_mul_f32 v[220:221], v[140:141], v[140:141]
	v_pk_fma_f32 v[220:221], v[136:137], v[136:137], v[220:221]
	v_pk_add_f32 v[20:21], v[20:21], v[220:221]
	v_pk_mul_f32 v[220:221], v[146:147], v[146:147]
	v_pk_fma_f32 v[220:221], v[142:143], v[142:143], v[220:221]
	v_pk_add_f32 v[16:17], v[16:17], v[220:221]
	v_pk_mul_f32 v[220:221], v[148:149], v[148:149]
	v_pk_fma_f32 v[220:221], v[144:145], v[144:145], v[220:221]
	v_pk_add_f32 v[14:15], v[14:15], v[220:221]
	v_pk_mul_f32 v[220:221], v[162:163], v[162:163]
	v_pk_fma_f32 v[220:221], v[158:159], v[158:159], v[220:221]
	v_pk_add_f32 v[12:13], v[12:13], v[220:221]
	v_pk_mul_f32 v[220:221], v[164:165], v[164:165]
	v_pk_fma_f32 v[220:221], v[160:161], v[160:161], v[220:221]
	v_pk_add_f32 v[10:11], v[10:11], v[220:221]
	s_waitcnt vmcnt(0)
	v_pk_mul_f32 v[220:221], v[170:171], v[170:171]
	v_pk_fma_f32 v[220:221], v[166:167], v[166:167], v[220:221]
	v_pk_add_f32 v[18:19], v[18:19], v[220:221]
	v_pk_mul_f32 v[220:221], v[172:173], v[172:173]
	v_pk_fma_f32 v[220:221], v[168:169], v[168:169], v[220:221]
	v_pk_add_f32 v[24:25], v[24:25], v[220:221]
	v_pk_mul_f32 v[220:221], v[178:179], v[178:179]
	v_pk_fma_f32 v[220:221], v[174:175], v[174:175], v[220:221]
	v_pk_add_f32 v[22:23], v[22:23], v[220:221]
	v_pk_mul_f32 v[220:221], v[180:181], v[180:181]
	v_pk_fma_f32 v[220:221], v[176:177], v[176:177], v[220:221]
	v_pk_add_f32 v[20:21], v[20:21], v[220:221]
	v_pk_mul_f32 v[220:221], v[198:199], v[198:199]
	v_pk_fma_f32 v[220:221], v[182:183], v[182:183], v[220:221]
	v_pk_add_f32 v[16:17], v[16:17], v[220:221]
	v_pk_mul_f32 v[220:221], v[200:201], v[200:201]
	v_pk_fma_f32 v[220:221], v[184:185], v[184:185], v[220:221]
	v_pk_add_f32 v[14:15], v[14:15], v[220:221]
	v_pk_mul_f32 v[220:221], v[206:207], v[206:207]
	v_pk_fma_f32 v[220:221], v[202:203], v[202:203], v[220:221]
	v_pk_add_f32 v[12:13], v[12:13], v[220:221]
	v_pk_mul_f32 v[220:221], v[208:209], v[208:209]
	v_pk_fma_f32 v[220:221], v[204:205], v[204:205], v[220:221]
	v_pk_add_f32 v[10:11], v[10:11], v[220:221]
	v_and_b32_e32 v3, 64, v28
	v_add_u32_e32 v3, 64, v3
	v_xor_b32_e32 v7, 16, v28
	v_cmp_lt_i32_e32 vcc, v7, v3
	s_nop 1
	v_cndmask_b32_e32 v7, v28, v7, vcc
	v_lshlrev_b32_e32 v29, 2, v7
	ds_bpermute_b32 v30, v29, v18
	ds_bpermute_b32 v31, v29, v19
	v_xor_b32_e32 v7, 8, v28
	v_cmp_lt_i32_e32 vcc, v7, v3
	ds_bpermute_b32 v32, v29, v24
	ds_bpermute_b32 v33, v29, v25
	v_cndmask_b32_e32 v7, v28, v7, vcc
	v_lshlrev_b32_e32 v34, 2, v7
	s_waitcnt lgkmcnt(2)
	v_pk_add_f32 v[18:19], v[18:19], v[30:31]
	ds_bpermute_b32 v30, v34, v18
	ds_bpermute_b32 v31, v34, v19
	v_xor_b32_e32 v7, 4, v28
	v_cmp_lt_i32_e32 vcc, v7, v3
	s_waitcnt lgkmcnt(2)
	v_pk_add_f32 v[24:25], v[24:25], v[32:33]
	ds_bpermute_b32 v32, v34, v24
	v_cndmask_b32_e32 v7, v28, v7, vcc
	v_lshlrev_b32_e32 v35, 2, v7
	s_waitcnt lgkmcnt(1)
	v_pk_add_f32 v[18:19], v[18:19], v[30:31]
	ds_bpermute_b32 v30, v35, v18
	ds_bpermute_b32 v31, v35, v19
	v_xor_b32_e32 v7, 2, v28
	v_cmp_lt_i32_e32 vcc, v7, v3
	ds_bpermute_b32 v33, v34, v25
	s_waitcnt lgkmcnt(1)
	v_pk_add_f32 v[18:19], v[18:19], v[30:31]
	v_cndmask_b32_e32 v7, v28, v7, vcc
	v_lshlrev_b32_e32 v36, 2, v7
	ds_bpermute_b32 v30, v36, v18
	ds_bpermute_b32 v31, v36, v19
	v_xor_b32_e32 v7, 1, v28
	v_cmp_lt_i32_e32 vcc, v7, v3
	s_waitcnt lgkmcnt(2)
	v_pk_add_f32 v[24:25], v[24:25], v[32:33]
	ds_bpermute_b32 v32, v35, v24
	v_cndmask_b32_e32 v3, v28, v7, vcc
	v_lshlrev_b32_e32 v37, 2, v3
	s_waitcnt lgkmcnt(1)
	v_pk_add_f32 v[18:19], v[18:19], v[30:31]
	ds_bpermute_b32 v30, v37, v18
	ds_bpermute_b32 v31, v37, v19
	ds_bpermute_b32 v33, v35, v25
	s_waitcnt lgkmcnt(1)
	v_pk_add_f32 v[30:31], v[18:19], v[30:31]
	v_mov_b64_e32 v[18:19], s[6:7]
	v_pk_fma_f32 v[30:31], v[30:31], s[4:5], v[18:19] op_sel_hi:[1,0,0]
	s_waitcnt lgkmcnt(0)
	v_pk_add_f32 v[24:25], v[24:25], v[32:33]
	v_mul_f32_e32 v3, 0x4b800000, v30
	v_cmp_gt_f32_e32 vcc, s11, v30
	ds_bpermute_b32 v32, v36, v24
	ds_bpermute_b32 v33, v36, v25
	v_cndmask_b32_e32 v3, v30, v3, vcc
	v_rsq_f32_e32 v3, v3
	s_waitcnt lgkmcnt(0)
	v_pk_add_f32 v[24:25], v[24:25], v[32:33]
	v_mul_f32_e32 v7, 0x45800000, v3
	v_cndmask_b32_e32 v3, v3, v7, vcc
	v_mul_f32_e32 v7, 0x4b800000, v31
	v_cmp_gt_f32_e32 vcc, s11, v31
	ds_bpermute_b32 v32, v29, v22
	ds_bpermute_b32 v33, v29, v23
	v_cndmask_b32_e32 v7, v31, v7, vcc
	ds_bpermute_b32 v30, v37, v24
	ds_bpermute_b32 v31, v37, v25
	v_rsq_f32_e32 v7, v7
	s_waitcnt lgkmcnt(2)
	v_pk_add_f32 v[22:23], v[22:23], v[32:33]
	ds_bpermute_b32 v33, v29, v21
	v_mul_f32_e32 v3, 0x3f4ccccd, v3
	s_waitcnt lgkmcnt(1)
	v_pk_add_f32 v[24:25], v[24:25], v[30:31]
	ds_bpermute_b32 v30, v34, v22
	ds_bpermute_b32 v31, v34, v23
	v_pk_fma_f32 v[24:25], v[24:25], s[4:5], v[18:19] op_sel_hi:[1,0,0]
	v_mul_f32_e32 v38, 0x45800000, v7
	v_mul_f32_e32 v32, 0x4b800000, v24
	v_cmp_gt_f32_e64 s[0:1], s11, v24
	s_waitcnt lgkmcnt(0)
	v_pk_add_f32 v[22:23], v[22:23], v[30:31]
	ds_bpermute_b32 v30, v35, v22
	ds_bpermute_b32 v31, v35, v23
	v_cndmask_b32_e64 v24, v24, v32, s[0:1]
	v_rsq_f32_e32 v24, v24
	v_cndmask_b32_e32 v7, v7, v38, vcc
	v_cmp_gt_f32_e32 vcc, s11, v25
	s_waitcnt lgkmcnt(0)
; __global__ void __launch_bounds__(512, 2) fwd_megakernel(const Params p) {
;     ...
;         for (int r = 0; r < 16; ++r) {
; #pragma unroll
;           for (int s = 16; s >= 1; s >>= 1) ssq[r] += __shfl_xor(ssq[r], s);
;           ssq[r] = rsqrtf(ssq[r] * (1.f / 256.f) + 1e-5f) * 0.8f; }
	v_pk_add_f32 v[22:23], v[22:23], v[30:31]
	ds_bpermute_b32 v30, v36, v22
	ds_bpermute_b32 v31, v36, v23
	v_mul_f32_e32 v32, 0x45800000, v24
	v_cndmask_b32_e64 v38, v24, v32, s[0:1]
	v_mul_f32_e32 v24, 0x4b800000, v25
	v_cndmask_b32_e32 v24, v25, v24, vcc
	v_rsq_f32_e32 v39, v24
	s_waitcnt lgkmcnt(0)
	v_pk_add_f32 v[24:25], v[22:23], v[30:31]
	ds_bpermute_b32 v32, v29, v20
	ds_bpermute_b32 v30, v37, v24
	ds_bpermute_b32 v31, v37, v25
	v_mul_f32_e32 v23, 0x45800000, v39
	v_mul_f32_e32 v22, 0x3f4ccccd, v38
	s_waitcnt lgkmcnt(2)
	v_pk_add_f32 v[20:21], v[20:21], v[32:33]
	v_mul_f32_e32 v7, 0x3f4ccccd, v7
	s_waitcnt lgkmcnt(0)
	v_pk_add_f32 v[24:25], v[24:25], v[30:31]
	ds_bpermute_b32 v30, v34, v20
	ds_bpermute_b32 v31, v34, v21
	v_pk_fma_f32 v[24:25], v[24:25], s[4:5], v[18:19] op_sel_hi:[1,0,0]
	s_waitcnt lgkmcnt(0)
	v_pk_add_f32 v[30:31], v[20:21], v[30:31]
	v_mul_f32_e32 v32, 0x4b800000, v24
	v_cmp_gt_f32_e64 s[0:1], s11, v24
	ds_bpermute_b32 v33, v35, v31
	v_cndmask_b32_e32 v20, v39, v23, vcc
	v_cndmask_b32_e64 v24, v24, v32, s[0:1]
	ds_bpermute_b32 v32, v35, v30
	v_rsq_f32_e32 v24, v24
	v_mul_f32_e32 v23, 0x4b800000, v25
	v_cmp_gt_f32_e32 vcc, s11, v25
	v_mul_f32_e32 v20, 0x3f4ccccd, v20
	s_waitcnt lgkmcnt(0)
	v_pk_add_f32 v[30:31], v[30:31], v[32:33]
	ds_bpermute_b32 v32, v36, v30
	ds_bpermute_b32 v33, v36, v31
	v_mul_f32_e32 v21, 0x45800000, v24
	v_cndmask_b32_e64 v21, v24, v21, s[0:1]
	v_cndmask_b32_e32 v23, v25, v23, vcc
	v_rsq_f32_e32 v23, v23
	s_waitcnt lgkmcnt(0)
	v_pk_add_f32 v[24:25], v[30:31], v[32:33]
	ds_bpermute_b32 v32, v29, v16
	ds_bpermute_b32 v33, v29, v17
	ds_bpermute_b32 v30, v37, v24
	ds_bpermute_b32 v31, v37, v25
	v_mul_f32_e32 v38, 0x45800000, v23
	v_mul_f32_e32 v21, 0x3f4ccccd, v21
	s_waitcnt lgkmcnt(2)
	v_pk_add_f32 v[16:17], v[16:17], v[32:33]
	s_waitcnt lgkmcnt(0)
	v_pk_add_f32 v[24:25], v[24:25], v[30:31]
	ds_bpermute_b32 v30, v34, v16
	ds_bpermute_b32 v31, v34, v17
	v_pk_fma_f32 v[24:25], v[24:25], s[4:5], v[18:19] op_sel_hi:[1,0,0]
	s_waitcnt lgkmcnt(0)
	v_pk_add_f32 v[30:31], v[16:17], v[30:31]
	v_mul_f32_e32 v32, 0x4b800000, v24
	v_cmp_gt_f32_e64 s[0:1], s11, v24
	ds_bpermute_b32 v33, v35, v31
	v_cndmask_b32_e32 v16, v23, v38, vcc
	v_cndmask_b32_e64 v24, v24, v32, s[0:1]
	ds_bpermute_b32 v32, v35, v30
	v_rsq_f32_e32 v24, v24
	v_mul_f32_e32 v23, 0x4b800000, v25
	v_cmp_gt_f32_e32 vcc, s11, v25
	v_mul_f32_e32 v16, 0x3f4ccccd, v16
	s_waitcnt lgkmcnt(0)
	v_pk_add_f32 v[30:31], v[30:31], v[32:33]
	ds_bpermute_b32 v32, v36, v30
	ds_bpermute_b32 v33, v36, v31
	v_mul_f32_e32 v17, 0x45800000, v24
	v_cndmask_b32_e64 v17, v24, v17, s[0:1]
	v_cndmask_b32_e32 v23, v25, v23, vcc
	v_rsq_f32_e32 v23, v23
	s_waitcnt lgkmcnt(0)
	v_pk_add_f32 v[24:25], v[30:31], v[32:33]
	ds_bpermute_b32 v32, v29, v14
	ds_bpermute_b32 v33, v29, v15
	ds_bpermute_b32 v30, v37, v24
	ds_bpermute_b32 v31, v37, v25
	v_mul_f32_e32 v38, 0x45800000, v23
	v_mul_f32_e32 v17, 0x3f4ccccd, v17
	s_waitcnt lgkmcnt(2)
	v_pk_add_f32 v[14:15], v[14:15], v[32:33]
	s_waitcnt lgkmcnt(0)
	v_pk_add_f32 v[24:25], v[24:25], v[30:31]
	ds_bpermute_b32 v30, v34, v14
	ds_bpermute_b32 v31, v34, v15
	v_pk_fma_f32 v[24:25], v[24:25], s[4:5], v[18:19] op_sel_hi:[1,0,0]
	s_waitcnt lgkmcnt(0)
	v_pk_add_f32 v[30:31], v[14:15], v[30:31]
	v_mul_f32_e32 v32, 0x4b800000, v24
	v_cmp_gt_f32_e64 s[0:1], s11, v24
	ds_bpermute_b32 v33, v35, v31
	v_cndmask_b32_e32 v14, v23, v38, vcc
	v_cndmask_b32_e64 v24, v24, v32, s[0:1]
	ds_bpermute_b32 v32, v35, v30
	v_rsq_f32_e32 v24, v24
	v_mul_f32_e32 v23, 0x4b800000, v25
	v_cmp_gt_f32_e32 vcc, s11, v25
	v_mul_f32_e32 v14, 0x3f4ccccd, v14
	s_waitcnt lgkmcnt(0)
	v_pk_add_f32 v[30:31], v[30:31], v[32:33]
	ds_bpermute_b32 v32, v36, v30
	ds_bpermute_b32 v33, v36, v31
	v_mul_f32_e32 v15, 0x45800000, v24
	v_cndmask_b32_e64 v15, v24, v15, s[0:1]
	v_cndmask_b32_e32 v23, v25, v23, vcc
	v_rsq_f32_e32 v23, v23
	s_waitcnt lgkmcnt(0)
	v_pk_add_f32 v[24:25], v[30:31], v[32:33]
	ds_bpermute_b32 v32, v29, v12
	ds_bpermute_b32 v33, v29, v13
	ds_bpermute_b32 v30, v37, v24
	ds_bpermute_b32 v31, v37, v25
	v_mul_f32_e32 v38, 0x45800000, v23
	v_mul_f32_e32 v15, 0x3f4ccccd, v15
	s_waitcnt lgkmcnt(2)
	v_pk_add_f32 v[12:13], v[12:13], v[32:33]
	s_waitcnt lgkmcnt(0)
	v_pk_add_f32 v[24:25], v[24:25], v[30:31]
	ds_bpermute_b32 v30, v34, v12
	ds_bpermute_b32 v31, v34, v13
	v_pk_fma_f32 v[24:25], v[24:25], s[4:5], v[18:19] op_sel_hi:[1,0,0]
	s_waitcnt lgkmcnt(0)
	v_pk_add_f32 v[30:31], v[12:13], v[30:31]
	v_mul_f32_e32 v32, 0x4b800000, v24
	v_cmp_gt_f32_e64 s[0:1], s11, v24
	ds_bpermute_b32 v33, v35, v31
	v_cndmask_b32_e32 v12, v23, v38, vcc
	v_cndmask_b32_e64 v24, v24, v32, s[0:1]
	ds_bpermute_b32 v32, v35, v30
	v_rsq_f32_e32 v24, v24
	v_mul_f32_e32 v23, 0x4b800000, v25
	v_cmp_gt_f32_e32 vcc, s11, v25
	v_mul_f32_e32 v12, 0x3f4ccccd, v12
	s_waitcnt lgkmcnt(0)
	v_pk_add_f32 v[30:31], v[30:31], v[32:33]
	ds_bpermute_b32 v32, v36, v30
	ds_bpermute_b32 v33, v36, v31
	v_mul_f32_e32 v13, 0x45800000, v24
	v_cndmask_b32_e64 v13, v24, v13, s[0:1]
	v_cndmask_b32_e32 v23, v25, v23, vcc
	v_rsq_f32_e32 v23, v23
	s_waitcnt lgkmcnt(0)
	v_pk_add_f32 v[24:25], v[30:31], v[32:33]
	ds_bpermute_b32 v32, v29, v10
	ds_bpermute_b32 v33, v29, v11
	ds_bpermute_b32 v30, v37, v24
	ds_bpermute_b32 v31, v37, v25
	v_mul_f32_e32 v29, 0x45800000, v23
	v_cndmask_b32_e32 v23, v23, v29, vcc
	s_waitcnt lgkmcnt(2)
	v_pk_add_f32 v[10:11], v[10:11], v[32:33]
	v_mul_f32_e32 v13, 0x3f4ccccd, v13
	s_waitcnt lgkmcnt(0)
	v_pk_add_f32 v[24:25], v[24:25], v[30:31]
	ds_bpermute_b32 v30, v34, v10
	ds_bpermute_b32 v31, v34, v11
	v_pk_fma_f32 v[24:25], v[24:25], s[4:5], v[18:19] op_sel_hi:[1,0,0]
	v_mul_f32_e32 v23, 0x3f4ccccd, v23
	v_mul_f32_e32 v32, 0x4b800000, v24
	v_cmp_gt_f32_e64 s[0:1], s11, v24
	s_waitcnt lgkmcnt(0)
; __device__ __forceinline__ bf16_t f2bf(float f) { return (bf16_t)(cvt_pk_bf16(f, 0.f) & 0xffffu); }
; #define EPI_FENCE() asm volatile("" ::: "memory")
; __global__ void __launch_bounds__(512, 2) fwd_megakernel(const Params p) {
;     ...
;         const float* gd = p.in[I_GDIFF];
;         char* wl = (char*)shm + wid * 16384;
; #pragma unroll 1
;         for (int d = 0; d < 4; ++d) { const float glo = gd[d * 32 + r32], ghi = gd[128 + d * 32 + r32];
; #pragma unroll
;           for (int q = 0; q < 4; ++q) { const f32x4 lo = scr[(d * 4 + q) * 64], hv = scr[4 * 1024 + (d * 4 + q) * 64];
; #pragma unroll
;             for (int j = 0; j < 4; ++j) { const int r = 4 * q + j; bf16_t* lp = (bf16_t*)(wl + (j + 8 * q + 4 * hi) * 512) + d * 32 + r32;
;               lp[0] = f2bf(lo[j] * ssq[r] * glo); lp[128] = f2bf(hv[j] * ssq[r] * ghi); } }
;           EPI_FENCE(); }
	v_pk_add_f32 v[10:11], v[10:11], v[30:31]
	ds_bpermute_b32 v30, v35, v10
	ds_bpermute_b32 v31, v35, v11
	v_cndmask_b32_e64 v24, v24, v32, s[0:1]
	v_rsq_f32_e32 v24, v24
	v_cmp_gt_f32_e32 vcc, s11, v25
	s_waitcnt lgkmcnt(0)
	v_pk_add_f32 v[10:11], v[10:11], v[30:31]
	ds_bpermute_b32 v30, v36, v10
	ds_bpermute_b32 v31, v36, v11
	v_mul_f32_e32 v29, 0x45800000, v24
	v_cndmask_b32_e64 v24, v24, v29, s[0:1]
	v_mul_f32_e32 v29, 0x4b800000, v25
	v_cndmask_b32_e32 v25, v25, v29, vcc
	s_waitcnt lgkmcnt(0)
	v_pk_add_f32 v[10:11], v[10:11], v[30:31]
	ds_bpermute_b32 v30, v37, v10
	ds_bpermute_b32 v31, v37, v11
	v_rsq_f32_e32 v25, v25
	v_mul_f32_e32 v24, 0x3f4ccccd, v24
	s_waitcnt lgkmcnt(0)
	v_pk_add_f32 v[10:11], v[10:11], v[30:31]
	v_mul_f32_e32 v29, 0x45800000, v25
	v_pk_fma_f32 v[10:11], v[10:11], s[4:5], v[18:19] op_sel_hi:[1,0,0]
	v_cndmask_b32_e32 v25, v25, v29, vcc
	v_mul_f32_e32 v18, 0x4b800000, v10
	v_cmp_gt_f32_e32 vcc, s11, v10
	v_cmp_gt_f32_e64 s[0:1], s11, v11
	v_mul_f32_e32 v25, 0x3f4ccccd, v25
	v_cndmask_b32_e32 v10, v10, v18, vcc
	v_rsq_f32_e32 v10, v10
	v_mul_f32_e32 v18, 0x4b800000, v11
	v_cndmask_b32_e64 v11, v11, v18, s[0:1]
	v_rsq_f32_e32 v11, v11
	v_mul_f32_e32 v18, 0x45800000, v10
	v_cndmask_b32_e32 v10, v10, v18, vcc
	v_mul_f32_e32 v18, 0x3f4ccccd, v10
	v_mul_f32_e32 v10, 0x45800000, v11
	v_cndmask_b32_e64 v10, v11, v10, s[0:1]
	v_mul_f32_e32 v19, 0x3f4ccccd, v10
	s_mov_b64 s[0:1], 0
	v_mov_b64_e32 v[10:11], v[4:5]
	v_mov_b32_e32 v29, v26
	global_load_dword v222, v[10:11], off offset:-512
	global_load_dword v223, v[10:11], off offset:0
	global_load_dword v224, v[10:11], off offset:-384
	global_load_dword v225, v[10:11], off offset:128
	global_load_dword v226, v[10:11], off offset:-256
	global_load_dword v227, v[10:11], off offset:256
	global_load_dword v228, v[10:11], off offset:-128
	global_load_dword v229, v[10:11], off offset:384
	s_waitcnt vmcnt(0)
	v_mul_f32_e32 v30, v62, v3
	v_mul_f32_e32 v30, v222, v30
	v_cvt_pk_bf16_f32 v30, v30, v157
	v_mul_f32_e32 v34, v66, v3
	v_mul_f32_e32 v31, v63, v7
	v_mul_f32_e32 v34, v223, v34
	ds_write_b16 v29, v30
	v_cvt_pk_bf16_f32 v30, v34, v157
	v_mul_f32_e32 v31, v222, v31
	v_mul_f32_e32 v35, v67, v7
	ds_write_b16 v29, v30 offset:256
	v_cvt_pk_bf16_f32 v30, v31, v157
	v_mul_f32_e32 v32, v64, v22
	v_mul_f32_e32 v35, v223, v35
	ds_write_b16 v29, v30 offset:512
	v_cvt_pk_bf16_f32 v30, v35, v157
	v_mul_f32_e32 v32, v222, v32
	v_mul_f32_e32 v36, v68, v22
	ds_write_b16 v29, v30 offset:768
	v_cvt_pk_bf16_f32 v30, v32, v157
	v_mul_f32_e32 v33, v65, v20
	v_mul_f32_e32 v37, v69, v20
	v_mul_f32_e32 v36, v223, v36
	ds_write_b16 v29, v30 offset:1024
	v_cvt_pk_bf16_f32 v30, v36, v157
	v_mul_f32_e32 v33, v222, v33
	v_mul_f32_e32 v37, v223, v37
	ds_write_b16 v29, v30 offset:1280
	v_cvt_pk_bf16_f32 v30, v33, v157
	ds_write_b16 v29, v30 offset:1536
	v_cvt_pk_bf16_f32 v44, v37, v157
	ds_write_b16 v29, v44 offset:1792
	v_mul_f32_e32 v30, v70, v21
	v_mul_f32_e32 v30, v222, v30
	v_mul_f32_e32 v34, v74, v21
	v_cvt_pk_bf16_f32 v30, v30, v157
	v_mul_f32_e32 v31, v71, v16
	v_mul_f32_e32 v34, v223, v34
	ds_write_b16 v29, v30 offset:4096
	v_cvt_pk_bf16_f32 v30, v34, v157
	v_mul_f32_e32 v35, v75, v16
	v_mul_f32_e32 v31, v222, v31
	ds_write_b16 v29, v30 offset:4352
	v_cvt_pk_bf16_f32 v30, v31, v157
	v_mul_f32_e32 v32, v72, v17
	v_mul_f32_e32 v35, v223, v35
	ds_write_b16 v29, v30 offset:4608
	v_cvt_pk_bf16_f32 v30, v35, v157
	v_mul_f32_e32 v36, v76, v17
	v_mul_f32_e32 v32, v222, v32
	ds_write_b16 v29, v30 offset:4864
	v_cvt_pk_bf16_f32 v30, v32, v157
	v_mul_f32_e32 v33, v73, v14
	v_mul_f32_e32 v37, v77, v14
	v_mul_f32_e32 v36, v223, v36
	ds_write_b16 v29, v30 offset:5120
	v_cvt_pk_bf16_f32 v30, v36, v157
	v_mul_f32_e32 v33, v222, v33
	v_mul_f32_e32 v37, v223, v37
	ds_write_b16 v29, v30 offset:5376
	v_cvt_pk_bf16_f32 v30, v33, v157
	ds_write_b16 v29, v30 offset:5632
	v_cvt_pk_bf16_f32 v44, v37, v157
	ds_write_b16 v29, v44 offset:5888
	v_mul_f32_e32 v30, v78, v15
	v_mul_f32_e32 v30, v222, v30
	v_mul_f32_e32 v34, v82, v15
	v_cvt_pk_bf16_f32 v30, v30, v157
	v_mul_f32_e32 v31, v79, v12
	v_mul_f32_e32 v34, v223, v34
	ds_write_b16 v29, v30 offset:8192
	v_cvt_pk_bf16_f32 v30, v34, v157
	v_mul_f32_e32 v35, v83, v12
	v_mul_f32_e32 v31, v222, v31
	ds_write_b16 v29, v30 offset:8448
	v_cvt_pk_bf16_f32 v30, v31, v157
	v_mul_f32_e32 v32, v80, v13
	v_mul_f32_e32 v35, v223, v35
	ds_write_b16 v29, v30 offset:8704
	v_cvt_pk_bf16_f32 v30, v35, v157
	v_mul_f32_e32 v36, v84, v13
	v_mul_f32_e32 v32, v222, v32
	ds_write_b16 v29, v30 offset:8960
	v_cvt_pk_bf16_f32 v30, v32, v157
	v_mul_f32_e32 v33, v81, v23
	v_mul_f32_e32 v37, v85, v23
	v_mul_f32_e32 v36, v223, v36
	ds_write_b16 v29, v30 offset:9216
	v_cvt_pk_bf16_f32 v30, v36, v157
	v_mul_f32_e32 v33, v222, v33
	v_mul_f32_e32 v37, v223, v37
	ds_write_b16 v29, v30 offset:9472
	v_cvt_pk_bf16_f32 v30, v33, v157
	ds_write_b16 v29, v30 offset:9728
	v_cvt_pk_bf16_f32 v44, v37, v157
	ds_write_b16 v29, v44 offset:9984
	v_mul_f32_e32 v30, v86, v24
	v_mul_f32_e32 v30, v222, v30
	v_mul_f32_e32 v34, v90, v24
	v_cvt_pk_bf16_f32 v30, v30, v157
	v_mul_f32_e32 v31, v87, v25
	v_mul_f32_e32 v34, v223, v34
	ds_write_b16 v29, v30 offset:12288
	v_cvt_pk_bf16_f32 v30, v34, v157
	v_mul_f32_e32 v35, v91, v25
	v_mul_f32_e32 v31, v222, v31
	ds_write_b16 v29, v30 offset:12544
	v_cvt_pk_bf16_f32 v30, v31, v157
	v_mul_f32_e32 v32, v88, v18
	v_mul_f32_e32 v35, v223, v35
	ds_write_b16 v29, v30 offset:12800
	v_cvt_pk_bf16_f32 v30, v35, v157
	v_mul_f32_e32 v36, v92, v18
	v_mul_f32_e32 v32, v222, v32
	ds_write_b16 v29, v30 offset:13056
	v_cvt_pk_bf16_f32 v30, v32, v157
	v_mul_f32_e32 v33, v89, v19
	v_mul_f32_e32 v36, v223, v36
; __device__ __forceinline__ bf16_t f2bf(float f) { return (bf16_t)(cvt_pk_bf16(f, 0.f) & 0xffffu); }
; #define EPI_FENCE() asm volatile("" ::: "memory")
; __global__ void __launch_bounds__(512, 2) fwd_megakernel(const Params p) {
;     ...
;         const float* gd = p.in[I_GDIFF];
;         char* wl = (char*)shm + wid * 16384;
; #pragma unroll 1
;         for (int d = 0; d < 4; ++d) { const float glo = gd[d * 32 + r32], ghi = gd[128 + d * 32 + r32];
; #pragma unroll
;           for (int q = 0; q < 4; ++q) { const f32x4 lo = scr[(d * 4 + q) * 64], hv = scr[4 * 1024 + (d * 4 + q) * 64];
; #pragma unroll
;             for (int j = 0; j < 4; ++j) { const int r = 4 * q + j; bf16_t* lp = (bf16_t*)(wl + (j + 8 * q + 4 * hi) * 512) + d * 32 + r32;
;               lp[0] = f2bf(lo[j] * ssq[r] * glo); lp[128] = f2bf(hv[j] * ssq[r] * ghi); } }
;           EPI_FENCE(); }
	ds_write_b16 v29, v30 offset:13312
	v_cvt_pk_bf16_f32 v30, v36, v157
	v_mul_f32_e32 v37, v93, v19
	v_mul_f32_e32 v33, v222, v33
	ds_write_b16 v29, v30 offset:13568
	v_cvt_pk_bf16_f32 v30, v33, v157
	v_mul_f32_e32 v37, v223, v37
	ds_write_b16 v29, v30 offset:13824
	v_cvt_pk_bf16_f32 v30, v37, v157
	ds_write_b16 v29, v30 offset:14080
	v_add_u32_e32 v29, 64, v29
	v_mul_f32_e32 v30, v94, v3
	v_mul_f32_e32 v30, v224, v30
	v_cvt_pk_bf16_f32 v30, v30, v157
	v_mul_f32_e32 v34, v98, v3
	v_mul_f32_e32 v31, v95, v7
	v_mul_f32_e32 v34, v225, v34
	ds_write_b16 v29, v30
	v_cvt_pk_bf16_f32 v30, v34, v157
	v_mul_f32_e32 v31, v224, v31
	v_mul_f32_e32 v35, v99, v7
	ds_write_b16 v29, v30 offset:256
	v_cvt_pk_bf16_f32 v30, v31, v157
	v_mul_f32_e32 v32, v96, v22
	v_mul_f32_e32 v35, v225, v35
	ds_write_b16 v29, v30 offset:512
	v_cvt_pk_bf16_f32 v30, v35, v157
	v_mul_f32_e32 v32, v224, v32
	v_mul_f32_e32 v36, v100, v22
	ds_write_b16 v29, v30 offset:768
	v_cvt_pk_bf16_f32 v30, v32, v157
	v_mul_f32_e32 v33, v97, v20
	v_mul_f32_e32 v37, v101, v20
	v_mul_f32_e32 v36, v225, v36
	ds_write_b16 v29, v30 offset:1024
	v_cvt_pk_bf16_f32 v30, v36, v157
	v_mul_f32_e32 v33, v224, v33
	v_mul_f32_e32 v37, v225, v37
	ds_write_b16 v29, v30 offset:1280
	v_cvt_pk_bf16_f32 v30, v33, v157
	ds_write_b16 v29, v30 offset:1536
	v_cvt_pk_bf16_f32 v44, v37, v157
	ds_write_b16 v29, v44 offset:1792
	v_mul_f32_e32 v30, v102, v21
	v_mul_f32_e32 v30, v224, v30
	v_mul_f32_e32 v34, v106, v21
	v_cvt_pk_bf16_f32 v30, v30, v157
	v_mul_f32_e32 v31, v103, v16
	v_mul_f32_e32 v34, v225, v34
	ds_write_b16 v29, v30 offset:4096
	v_cvt_pk_bf16_f32 v30, v34, v157
	v_mul_f32_e32 v35, v107, v16
	v_mul_f32_e32 v31, v224, v31
	ds_write_b16 v29, v30 offset:4352
	v_cvt_pk_bf16_f32 v30, v31, v157
	v_mul_f32_e32 v32, v104, v17
	v_mul_f32_e32 v35, v225, v35
	ds_write_b16 v29, v30 offset:4608
	v_cvt_pk_bf16_f32 v30, v35, v157
	v_mul_f32_e32 v36, v108, v17
	v_mul_f32_e32 v32, v224, v32
	ds_write_b16 v29, v30 offset:4864
	v_cvt_pk_bf16_f32 v30, v32, v157
	v_mul_f32_e32 v33, v105, v14
	v_mul_f32_e32 v37, v109, v14
	v_mul_f32_e32 v36, v225, v36
	ds_write_b16 v29, v30 offset:5120
	v_cvt_pk_bf16_f32 v30, v36, v157
	v_mul_f32_e32 v33, v224, v33
	v_mul_f32_e32 v37, v225, v37
	ds_write_b16 v29, v30 offset:5376
	v_cvt_pk_bf16_f32 v30, v33, v157
	ds_write_b16 v29, v30 offset:5632
	v_cvt_pk_bf16_f32 v44, v37, v157
	ds_write_b16 v29, v44 offset:5888
	v_mul_f32_e32 v30, v110, v15
	v_mul_f32_e32 v30, v224, v30
	v_mul_f32_e32 v34, v114, v15
	v_cvt_pk_bf16_f32 v30, v30, v157
	v_mul_f32_e32 v31, v111, v12
	v_mul_f32_e32 v34, v225, v34
	ds_write_b16 v29, v30 offset:8192
	v_cvt_pk_bf16_f32 v30, v34, v157
	v_mul_f32_e32 v35, v115, v12
	v_mul_f32_e32 v31, v224, v31
	ds_write_b16 v29, v30 offset:8448
	v_cvt_pk_bf16_f32 v30, v31, v157
	v_mul_f32_e32 v32, v112, v13
	v_mul_f32_e32 v35, v225, v35
	ds_write_b16 v29, v30 offset:8704
	v_cvt_pk_bf16_f32 v30, v35, v157
	v_mul_f32_e32 v36, v116, v13
	v_mul_f32_e32 v32, v224, v32
	ds_write_b16 v29, v30 offset:8960
	v_cvt_pk_bf16_f32 v30, v32, v157
	v_mul_f32_e32 v33, v113, v23
	v_mul_f32_e32 v37, v117, v23
	v_mul_f32_e32 v36, v225, v36
	ds_write_b16 v29, v30 offset:9216
	v_cvt_pk_bf16_f32 v30, v36, v157
	v_mul_f32_e32 v33, v224, v33
	v_mul_f32_e32 v37, v225, v37
	ds_write_b16 v29, v30 offset:9472
	v_cvt_pk_bf16_f32 v30, v33, v157
	ds_write_b16 v29, v30 offset:9728
	v_cvt_pk_bf16_f32 v44, v37, v157
	ds_write_b16 v29, v44 offset:9984
	v_mul_f32_e32 v30, v118, v24
	v_mul_f32_e32 v30, v224, v30
	v_mul_f32_e32 v34, v122, v24
	v_cvt_pk_bf16_f32 v30, v30, v157
	v_mul_f32_e32 v31, v119, v25
	v_mul_f32_e32 v34, v225, v34
	ds_write_b16 v29, v30 offset:12288
	v_cvt_pk_bf16_f32 v30, v34, v157
	v_mul_f32_e32 v35, v123, v25
	v_mul_f32_e32 v31, v224, v31
	ds_write_b16 v29, v30 offset:12544
	v_cvt_pk_bf16_f32 v30, v31, v157
	v_mul_f32_e32 v32, v120, v18
	v_mul_f32_e32 v35, v225, v35
	ds_write_b16 v29, v30 offset:12800
	v_cvt_pk_bf16_f32 v30, v35, v157
	v_mul_f32_e32 v36, v124, v18
	v_mul_f32_e32 v32, v224, v32
	ds_write_b16 v29, v30 offset:13056
	v_cvt_pk_bf16_f32 v30, v32, v157
	v_mul_f32_e32 v33, v121, v19
	v_mul_f32_e32 v36, v225, v36
	ds_write_b16 v29, v30 offset:13312
	v_cvt_pk_bf16_f32 v30, v36, v157
	v_mul_f32_e32 v37, v125, v19
	v_mul_f32_e32 v33, v224, v33
	ds_write_b16 v29, v30 offset:13568
	v_cvt_pk_bf16_f32 v30, v33, v157
	v_mul_f32_e32 v37, v225, v37
	ds_write_b16 v29, v30 offset:13824
	v_cvt_pk_bf16_f32 v30, v37, v157
	ds_write_b16 v29, v30 offset:14080
	v_add_u32_e32 v29, 64, v29
	v_mul_f32_e32 v30, v126, v3
	v_mul_f32_e32 v30, v226, v30
	v_cvt_pk_bf16_f32 v30, v30, v157
	v_mul_f32_e32 v34, v130, v3
	v_mul_f32_e32 v31, v127, v7
	v_mul_f32_e32 v34, v227, v34
	ds_write_b16 v29, v30
	v_cvt_pk_bf16_f32 v30, v34, v157
	v_mul_f32_e32 v31, v226, v31
	v_mul_f32_e32 v35, v131, v7
	ds_write_b16 v29, v30 offset:256
	v_cvt_pk_bf16_f32 v30, v31, v157
	v_mul_f32_e32 v32, v128, v22
	v_mul_f32_e32 v35, v227, v35
	ds_write_b16 v29, v30 offset:512
	v_cvt_pk_bf16_f32 v30, v35, v157
	v_mul_f32_e32 v32, v226, v32
	v_mul_f32_e32 v36, v132, v22
	ds_write_b16 v29, v30 offset:768
	v_cvt_pk_bf16_f32 v30, v32, v157
	v_mul_f32_e32 v33, v129, v20
	v_mul_f32_e32 v37, v133, v20
	v_mul_f32_e32 v36, v227, v36
	ds_write_b16 v29, v30 offset:1024
	v_cvt_pk_bf16_f32 v30, v36, v157
	v_mul_f32_e32 v33, v226, v33
	v_mul_f32_e32 v37, v227, v37
	ds_write_b16 v29, v30 offset:1280
	v_cvt_pk_bf16_f32 v30, v33, v157
	ds_write_b16 v29, v30 offset:1536
	v_cvt_pk_bf16_f32 v44, v37, v157
	ds_write_b16 v29, v44 offset:1792
	v_mul_f32_e32 v30, v134, v21
	v_mul_f32_e32 v30, v226, v30
	v_mul_f32_e32 v34, v138, v21
	v_cvt_pk_bf16_f32 v30, v30, v157
; __device__ __forceinline__ bf16_t f2bf(float f) { return (bf16_t)(cvt_pk_bf16(f, 0.f) & 0xffffu); }
; #define EPI_FENCE() asm volatile("" ::: "memory")
; __global__ void __launch_bounds__(512, 2) fwd_megakernel(const Params p) {
;     ...
;         const float* gd = p.in[I_GDIFF];
;         char* wl = (char*)shm + wid * 16384;
; #pragma unroll 1
;         for (int d = 0; d < 4; ++d) { const float glo = gd[d * 32 + r32], ghi = gd[128 + d * 32 + r32];
; #pragma unroll
;           for (int q = 0; q < 4; ++q) { const f32x4 lo = scr[(d * 4 + q) * 64], hv = scr[4 * 1024 + (d * 4 + q) * 64];
; #pragma unroll
;             for (int j = 0; j < 4; ++j) { const int r = 4 * q + j; bf16_t* lp = (bf16_t*)(wl + (j + 8 * q + 4 * hi) * 512) + d * 32 + r32;
;               lp[0] = f2bf(lo[j] * ssq[r] * glo); lp[128] = f2bf(hv[j] * ssq[r] * ghi); } }
;           EPI_FENCE(); }
	v_mul_f32_e32 v31, v135, v16
	v_mul_f32_e32 v34, v227, v34
	ds_write_b16 v29, v30 offset:4096
	v_cvt_pk_bf16_f32 v30, v34, v157
	v_mul_f32_e32 v35, v139, v16
	v_mul_f32_e32 v31, v226, v31
	ds_write_b16 v29, v30 offset:4352
	v_cvt_pk_bf16_f32 v30, v31, v157
	v_mul_f32_e32 v32, v136, v17
	v_mul_f32_e32 v35, v227, v35
	ds_write_b16 v29, v30 offset:4608
	v_cvt_pk_bf16_f32 v30, v35, v157
	v_mul_f32_e32 v36, v140, v17
	v_mul_f32_e32 v32, v226, v32
	ds_write_b16 v29, v30 offset:4864
	v_cvt_pk_bf16_f32 v30, v32, v157
	v_mul_f32_e32 v33, v137, v14
	v_mul_f32_e32 v37, v141, v14
	v_mul_f32_e32 v36, v227, v36
	ds_write_b16 v29, v30 offset:5120
	v_cvt_pk_bf16_f32 v30, v36, v157
	v_mul_f32_e32 v33, v226, v33
	v_mul_f32_e32 v37, v227, v37
	ds_write_b16 v29, v30 offset:5376
	v_cvt_pk_bf16_f32 v30, v33, v157
	ds_write_b16 v29, v30 offset:5632
	v_cvt_pk_bf16_f32 v44, v37, v157
	ds_write_b16 v29, v44 offset:5888
	v_mul_f32_e32 v30, v142, v15
	v_mul_f32_e32 v30, v226, v30
	v_mul_f32_e32 v34, v146, v15
	v_cvt_pk_bf16_f32 v30, v30, v157
	v_mul_f32_e32 v31, v143, v12
	v_mul_f32_e32 v34, v227, v34
	ds_write_b16 v29, v30 offset:8192
	v_cvt_pk_bf16_f32 v30, v34, v157
	v_mul_f32_e32 v35, v147, v12
	v_mul_f32_e32 v31, v226, v31
	ds_write_b16 v29, v30 offset:8448
	v_cvt_pk_bf16_f32 v30, v31, v157
	v_mul_f32_e32 v32, v144, v13
	v_mul_f32_e32 v35, v227, v35
	ds_write_b16 v29, v30 offset:8704
	v_cvt_pk_bf16_f32 v30, v35, v157
	v_mul_f32_e32 v36, v148, v13
	v_mul_f32_e32 v32, v226, v32
	ds_write_b16 v29, v30 offset:8960
	v_cvt_pk_bf16_f32 v30, v32, v157
	v_mul_f32_e32 v33, v145, v23
	v_mul_f32_e32 v37, v149, v23
	v_mul_f32_e32 v36, v227, v36
	ds_write_b16 v29, v30 offset:9216
	v_cvt_pk_bf16_f32 v30, v36, v157
	v_mul_f32_e32 v33, v226, v33
	v_mul_f32_e32 v37, v227, v37
	ds_write_b16 v29, v30 offset:9472
	v_cvt_pk_bf16_f32 v30, v33, v157
	ds_write_b16 v29, v30 offset:9728
	v_cvt_pk_bf16_f32 v44, v37, v157
	ds_write_b16 v29, v44 offset:9984
	v_mul_f32_e32 v30, v158, v24
	v_mul_f32_e32 v30, v226, v30
	v_mul_f32_e32 v34, v162, v24
	v_cvt_pk_bf16_f32 v30, v30, v157
	v_mul_f32_e32 v31, v159, v25
	v_mul_f32_e32 v34, v227, v34
	ds_write_b16 v29, v30 offset:12288
	v_cvt_pk_bf16_f32 v30, v34, v157
	v_mul_f32_e32 v35, v163, v25
	v_mul_f32_e32 v31, v226, v31
	ds_write_b16 v29, v30 offset:12544
	v_cvt_pk_bf16_f32 v30, v31, v157
	v_mul_f32_e32 v32, v160, v18
	v_mul_f32_e32 v35, v227, v35
	ds_write_b16 v29, v30 offset:12800
	v_cvt_pk_bf16_f32 v30, v35, v157
	v_mul_f32_e32 v36, v164, v18
	v_mul_f32_e32 v32, v226, v32
	ds_write_b16 v29, v30 offset:13056
	v_cvt_pk_bf16_f32 v30, v32, v157
	v_mul_f32_e32 v33, v161, v19
	v_mul_f32_e32 v36, v227, v36
	ds_write_b16 v29, v30 offset:13312
	v_cvt_pk_bf16_f32 v30, v36, v157
	v_mul_f32_e32 v37, v165, v19
	v_mul_f32_e32 v33, v226, v33
	ds_write_b16 v29, v30 offset:13568
	v_cvt_pk_bf16_f32 v30, v33, v157
	v_mul_f32_e32 v37, v227, v37
	ds_write_b16 v29, v30 offset:13824
	v_cvt_pk_bf16_f32 v30, v37, v157
	ds_write_b16 v29, v30 offset:14080
	v_add_u32_e32 v29, 64, v29
	v_mul_f32_e32 v30, v166, v3
	v_mul_f32_e32 v30, v228, v30
	v_cvt_pk_bf16_f32 v30, v30, v157
	v_mul_f32_e32 v34, v170, v3
	v_mul_f32_e32 v31, v167, v7
	v_mul_f32_e32 v34, v229, v34
	ds_write_b16 v29, v30
	v_cvt_pk_bf16_f32 v30, v34, v157
	v_mul_f32_e32 v31, v228, v31
	v_mul_f32_e32 v35, v171, v7
	ds_write_b16 v29, v30 offset:256
	v_cvt_pk_bf16_f32 v30, v31, v157
	v_mul_f32_e32 v32, v168, v22
	v_mul_f32_e32 v35, v229, v35
	ds_write_b16 v29, v30 offset:512
	v_cvt_pk_bf16_f32 v30, v35, v157
	v_mul_f32_e32 v32, v228, v32
	v_mul_f32_e32 v36, v172, v22
	ds_write_b16 v29, v30 offset:768
	v_cvt_pk_bf16_f32 v30, v32, v157
	v_mul_f32_e32 v33, v169, v20
	v_mul_f32_e32 v37, v173, v20
	v_mul_f32_e32 v36, v229, v36
	ds_write_b16 v29, v30 offset:1024
	v_cvt_pk_bf16_f32 v30, v36, v157
	v_mul_f32_e32 v33, v228, v33
	v_mul_f32_e32 v37, v229, v37
	ds_write_b16 v29, v30 offset:1280
	v_cvt_pk_bf16_f32 v30, v33, v157
	ds_write_b16 v29, v30 offset:1536
	v_cvt_pk_bf16_f32 v44, v37, v157
	ds_write_b16 v29, v44 offset:1792
	v_mul_f32_e32 v30, v174, v21
	v_mul_f32_e32 v30, v228, v30
	v_mul_f32_e32 v34, v178, v21
	v_cvt_pk_bf16_f32 v30, v30, v157
	v_mul_f32_e32 v31, v175, v16
	v_mul_f32_e32 v34, v229, v34
	ds_write_b16 v29, v30 offset:4096
	v_cvt_pk_bf16_f32 v30, v34, v157
	v_mul_f32_e32 v35, v179, v16
	v_mul_f32_e32 v31, v228, v31
	ds_write_b16 v29, v30 offset:4352
	v_cvt_pk_bf16_f32 v30, v31, v157
	v_mul_f32_e32 v32, v176, v17
	v_mul_f32_e32 v35, v229, v35
	ds_write_b16 v29, v30 offset:4608
	v_cvt_pk_bf16_f32 v30, v35, v157
	v_mul_f32_e32 v36, v180, v17
	v_mul_f32_e32 v32, v228, v32
	ds_write_b16 v29, v30 offset:4864
	v_cvt_pk_bf16_f32 v30, v32, v157
	v_mul_f32_e32 v33, v177, v14
	v_mul_f32_e32 v37, v181, v14
	v_mul_f32_e32 v36, v229, v36
	ds_write_b16 v29, v30 offset:5120
	v_cvt_pk_bf16_f32 v30, v36, v157
	v_mul_f32_e32 v33, v228, v33
	v_mul_f32_e32 v37, v229, v37
	ds_write_b16 v29, v30 offset:5376
	v_cvt_pk_bf16_f32 v30, v33, v157
	ds_write_b16 v29, v30 offset:5632
	v_cvt_pk_bf16_f32 v44, v37, v157
	ds_write_b16 v29, v44 offset:5888
	v_mul_f32_e32 v30, v182, v15
	v_mul_f32_e32 v30, v228, v30
	v_mul_f32_e32 v34, v198, v15
	v_cvt_pk_bf16_f32 v30, v30, v157
	v_mul_f32_e32 v31, v183, v12
	v_mul_f32_e32 v34, v229, v34
	ds_write_b16 v29, v30 offset:8192
	v_cvt_pk_bf16_f32 v30, v34, v157
	v_mul_f32_e32 v35, v199, v12
	v_mul_f32_e32 v31, v228, v31
	ds_write_b16 v29, v30 offset:8448
	v_cvt_pk_bf16_f32 v30, v31, v157
	v_mul_f32_e32 v32, v184, v13
	v_mul_f32_e32 v35, v229, v35
	ds_write_b16 v29, v30 offset:8704
	v_cvt_pk_bf16_f32 v30, v35, v157
; __device__ __forceinline__ bf16_t f2bf(float f) { return (bf16_t)(cvt_pk_bf16(f, 0.f) & 0xffffu); }
; #define EPI_FENCE() asm volatile("" ::: "memory")
; __global__ void __launch_bounds__(512, 2) fwd_megakernel(const Params p) {
;     ...
;         for (int d = 0; d < 4; ++d) { const float glo = gd[d * 32 + r32], ghi = gd[128 + d * 32 + r32];
; #pragma unroll
;           for (int q = 0; q < 4; ++q) { const f32x4 lo = scr[(d * 4 + q) * 64], hv = scr[4 * 1024 + (d * 4 + q) * 64];
; #pragma unroll
;             for (int j = 0; j < 4; ++j) { const int r = 4 * q + j; bf16_t* lp = (bf16_t*)(wl + (j + 8 * q + 4 * hi) * 512) + d * 32 + r32;
;               lp[0] = f2bf(lo[j] * ssq[r] * glo); lp[128] = f2bf(hv[j] * ssq[r] * ghi); } }
;           EPI_FENCE(); }
;         bf16_t* Ow = (bf16_t*)(ws + O_ATT) + (rowq + wid * 32 + (lane >> 5)) * 2048 + 1024 + h * 256 + (lane & 31) * 8;
; #pragma unroll
;         for (int k = 0; k < 16; ++k) { const u32x4 v = *(const u32x4*)(wl + (k * 2 + (lane >> 5)) * 512 + (lane & 31) * 16); *(u32x4*)(Ow + (size_t)(k * 2) * 2048) = v; }
	v_mul_f32_e32 v36, v200, v13
	v_mul_f32_e32 v32, v228, v32
	ds_write_b16 v29, v30 offset:8960
	v_cvt_pk_bf16_f32 v30, v32, v157
	v_mul_f32_e32 v33, v185, v23
	v_mul_f32_e32 v37, v201, v23
	v_mul_f32_e32 v36, v229, v36
	ds_write_b16 v29, v30 offset:9216
	v_cvt_pk_bf16_f32 v30, v36, v157
	v_mul_f32_e32 v33, v228, v33
	v_mul_f32_e32 v37, v229, v37
	ds_write_b16 v29, v30 offset:9472
	v_cvt_pk_bf16_f32 v30, v33, v157
	ds_write_b16 v29, v30 offset:9728
	v_cvt_pk_bf16_f32 v44, v37, v157
	ds_write_b16 v29, v44 offset:9984
	v_mul_f32_e32 v30, v202, v24
	v_mul_f32_e32 v30, v228, v30
	v_mul_f32_e32 v34, v206, v24
	v_cvt_pk_bf16_f32 v30, v30, v157
	v_mul_f32_e32 v31, v203, v25
	v_mul_f32_e32 v34, v229, v34
	ds_write_b16 v29, v30 offset:12288
	v_cvt_pk_bf16_f32 v30, v34, v157
	v_mul_f32_e32 v35, v207, v25
	v_mul_f32_e32 v31, v228, v31
	ds_write_b16 v29, v30 offset:12544
	v_cvt_pk_bf16_f32 v30, v31, v157
	v_mul_f32_e32 v32, v204, v18
	v_mul_f32_e32 v35, v229, v35
	ds_write_b16 v29, v30 offset:12800
	v_cvt_pk_bf16_f32 v30, v35, v157
	v_mul_f32_e32 v36, v208, v18
	v_mul_f32_e32 v32, v228, v32
	ds_write_b16 v29, v30 offset:13056
	v_cvt_pk_bf16_f32 v30, v32, v157
	v_mul_f32_e32 v33, v205, v19
	v_mul_f32_e32 v36, v229, v36
	ds_write_b16 v29, v30 offset:13312
	v_cvt_pk_bf16_f32 v30, v36, v157
	v_mul_f32_e32 v37, v209, v19
	v_mul_f32_e32 v33, v228, v33
	ds_write_b16 v29, v30 offset:13568
	v_cvt_pk_bf16_f32 v30, v33, v157
	v_mul_f32_e32 v37, v229, v37
	ds_write_b16 v29, v30 offset:13824
	v_cvt_pk_bf16_f32 v30, v37, v157
	ds_write_b16 v29, v30 offset:14080
	v_add_u32_e32 v29, 64, v29
	s_ashr_i32 s1, s38, 3
	s_and_b32 s0, s38, 4
	s_and_b32 s1, s1, -8
	s_or_b32 s0, s1, s0
	s_ashr_i32 s0, s0, 2
	s_ashr_i32 s1, s0, 31
	s_and_b32 s2, s38, 56
	s_lshl_b64 s[0:1], s[0:1], 11
	v_add_lshl_u32 v156, v193, s2, 5
	v_lshl_add_u64 v[8:9], s[0:1], 0, v[156:157]
	v_or_b32_e32 v8, v8, v154
	v_lshlrev_b64 v[8:9], 12, v[8:9]
	s_lshl_b32 s0, s38, 9
	v_lshl_add_u64 v[8:9], s[74:75], 0, v[8:9]
	s_and_b32 s2, s0, 0x600
	v_lshl_add_u64 v[8:9], v[8:9], 0, s[2:3]
	v_mov_b32_e32 v7, v157
	v_lshl_add_u64 v[16:17], v[8:9], 0, v[6:7]
	ds_read_b128 v[8:11], v27
	ds_read_b128 v[12:15], v27 offset:1024
	v_add_co_u32_e32 v18, vcc, s15, v16
	s_add_i32 s38, s38, s78
	s_nop 0
	v_addc_co_u32_e32 v19, vcc, 0, v17, vcc
	s_waitcnt lgkmcnt(1)
	global_store_dwordx4 v[18:19], v[8:11], off offset:2048
	s_cmpk_gt_i32 s38, 0xff
	v_add_u32_e32 v2, s5, v2
	v_add_co_u32_e32 v8, vcc, s16, v16
	s_nop 1
	v_addc_co_u32_e32 v9, vcc, 0, v17, vcc
	s_waitcnt lgkmcnt(0)
	global_store_dwordx4 v[8:9], v[12:15], off offset:2048
	ds_read_b128 v[8:11], v27 offset:2048
	ds_read_b128 v[12:15], v27 offset:3072
	v_add_co_u32_e32 v18, vcc, s17, v16
	s_nop 1
	v_addc_co_u32_e32 v19, vcc, 0, v17, vcc
	s_waitcnt lgkmcnt(1)
	global_store_dwordx4 v[18:19], v[8:11], off offset:2048
	s_nop 1
	v_add_co_u32_e32 v8, vcc, s18, v16
	s_nop 1
	v_addc_co_u32_e32 v9, vcc, 0, v17, vcc
	s_waitcnt lgkmcnt(0)
	global_store_dwordx4 v[8:9], v[12:15], off offset:2048
	ds_read_b128 v[8:11], v27 offset:4096
	ds_read_b128 v[12:15], v27 offset:5120
	v_add_co_u32_e32 v18, vcc, s19, v16
	s_nop 1
	v_addc_co_u32_e32 v19, vcc, 0, v17, vcc
	s_waitcnt lgkmcnt(1)
	global_store_dwordx4 v[18:19], v[8:11], off offset:2048
	s_nop 1
	v_add_co_u32_e32 v8, vcc, s20, v16
	s_nop 1
	v_addc_co_u32_e32 v9, vcc, 0, v17, vcc
	s_waitcnt lgkmcnt(0)
	global_store_dwordx4 v[8:9], v[12:15], off offset:2048
	ds_read_b128 v[8:11], v27 offset:6144
	ds_read_b128 v[12:15], v27 offset:7168
	v_add_co_u32_e32 v18, vcc, s21, v16
	s_nop 1
	v_addc_co_u32_e32 v19, vcc, 0, v17, vcc
	s_waitcnt lgkmcnt(1)
	global_store_dwordx4 v[18:19], v[8:11], off offset:2048
	s_nop 1
	v_add_co_u32_e32 v8, vcc, s22, v16
	s_nop 1
	v_addc_co_u32_e32 v9, vcc, 0, v17, vcc
	s_waitcnt lgkmcnt(0)
	global_store_dwordx4 v[8:9], v[12:15], off offset:2048
	ds_read_b128 v[8:11], v27 offset:8192
	ds_read_b128 v[12:15], v27 offset:9216
	v_add_co_u32_e32 v18, vcc, s23, v16
	s_nop 1
	v_addc_co_u32_e32 v19, vcc, 0, v17, vcc
	s_waitcnt lgkmcnt(1)
	global_store_dwordx4 v[18:19], v[8:11], off offset:2048
	s_nop 1
	v_add_co_u32_e32 v8, vcc, s28, v16
	s_nop 1
	v_addc_co_u32_e32 v9, vcc, 0, v17, vcc
	s_waitcnt lgkmcnt(0)
	global_store_dwordx4 v[8:9], v[12:15], off offset:2048
	ds_read_b128 v[8:11], v27 offset:10240
	ds_read_b128 v[12:15], v27 offset:11264
	v_add_co_u32_e32 v18, vcc, s29, v16
	s_nop 1
	v_addc_co_u32_e32 v19, vcc, 0, v17, vcc
	s_waitcnt lgkmcnt(1)
	global_store_dwordx4 v[18:19], v[8:11], off offset:2048
	s_nop 1
	v_add_co_u32_e32 v8, vcc, s30, v16
	s_nop 1
	v_addc_co_u32_e32 v9, vcc, 0, v17, vcc
	s_waitcnt lgkmcnt(0)
	global_store_dwordx4 v[8:9], v[12:15], off offset:2048
	ds_read_b128 v[8:11], v27 offset:12288
	ds_read_b128 v[12:15], v27 offset:13312
	v_add_co_u32_e32 v18, vcc, s31, v16
	s_nop 1
	v_addc_co_u32_e32 v19, vcc, 0, v17, vcc
	s_waitcnt lgkmcnt(1)
	global_store_dwordx4 v[18:19], v[8:11], off offset:2048
	s_nop 1
	v_add_co_u32_e32 v8, vcc, s33, v16
	s_nop 1
	v_addc_co_u32_e32 v9, vcc, 0, v17, vcc
	s_waitcnt lgkmcnt(0)
	global_store_dwordx4 v[8:9], v[12:15], off offset:2048
	ds_read_b128 v[8:11], v27 offset:14336
	ds_read_b128 v[12:15], v27 offset:15360
	v_add_co_u32_e32 v18, vcc, 0x1a31c000, v16
	s_nop 1
	v_addc_co_u32_e32 v19, vcc, 0, v17, vcc
	s_waitcnt lgkmcnt(1)
	global_store_dwordx4 v[18:19], v[8:11], off offset:2048
	s_nop 1
	v_add_co_u32_e32 v8, vcc, 0x1a31e000, v16
	s_nop 1
	v_addc_co_u32_e32 v9, vcc, 0, v17, vcc
	s_waitcnt lgkmcnt(0)
	global_store_dwordx4 v[8:9], v[12:15], off offset:2048
	s_cbranch_scc0 .LBB0_413
